# generic GEMM epilogue relu^2 path: redundant canonicalizing v_max x,x,x removed (120 VALU per wave per unit)
# speedup vs baseline: 1.0057x; 1.0057x over previous
.LBB0_1230:
	s_cmp_eq_u32 s19, 1
	s_cbranch_scc0 .LBB0_1232
	v_max_f32_e32 v118, 0, v118
	v_max_f32_e32 v119, 0, v119
	v_max_f32_e32 v120, 0, v120
	v_max_f32_e32 v121, 0, v121
	v_max_f32_e32 v114, 0, v114
	v_max_f32_e32 v115, 0, v115
	v_max_f32_e32 v116, 0, v116
	v_max_f32_e32 v117, 0, v117
	v_pk_mul_f32 v[118:119], v[118:119], v[118:119]
	v_pk_mul_f32 v[120:121], v[120:121], v[120:121]
	v_pk_mul_f32 v[114:115], v[114:115], v[114:115]
	v_pk_mul_f32 v[116:117], v[116:117], v[116:117]

.LBB0_1248:
	s_andn2_b64 vcc, exec, s[16:17]
	s_cbranch_vccnz .LBB0_1252
	s_cmp_eq_u32 s5, 1
	s_cbranch_scc0 .LBB0_1251
	v_max_f32_e32 v110, 0, v110
	v_max_f32_e32 v111, 0, v111
	v_max_f32_e32 v112, 0, v112
	v_max_f32_e32 v113, 0, v113
	v_max_f32_e32 v106, 0, v106
	v_max_f32_e32 v107, 0, v107
	v_max_f32_e32 v108, 0, v108
	v_max_f32_e32 v109, 0, v109
	v_pk_mul_f32 v[110:111], v[110:111], v[110:111]
	v_pk_mul_f32 v[112:113], v[112:113], v[112:113]
	v_pk_mul_f32 v[106:107], v[106:107], v[106:107]
	v_pk_mul_f32 v[108:109], v[108:109], v[108:109]

.LBB0_1258:
	s_cmp_eq_u32 s19, 1
	s_cbranch_scc0 .LBB0_1260
	v_max_f32_e32 v102, 0, v102
	v_max_f32_e32 v103, 0, v103
	v_max_f32_e32 v104, 0, v104
	v_max_f32_e32 v105, 0, v105
	v_max_f32_e32 v98, 0, v98
	v_max_f32_e32 v99, 0, v99
	v_max_f32_e32 v100, 0, v100
	v_max_f32_e32 v101, 0, v101
	v_pk_mul_f32 v[102:103], v[102:103], v[102:103]
	v_pk_mul_f32 v[104:105], v[104:105], v[104:105]
	v_pk_mul_f32 v[98:99], v[98:99], v[98:99]
	v_pk_mul_f32 v[100:101], v[100:101], v[100:101]

.LBB0_1276:
	s_andn2_b64 vcc, exec, s[16:17]
	s_cbranch_vccnz .LBB0_1280
	s_cmp_eq_u32 s5, 1
	s_cbranch_scc0 .LBB0_1279
	v_max_f32_e32 v94, 0, v94
	v_max_f32_e32 v95, 0, v95
	v_max_f32_e32 v96, 0, v96
	v_max_f32_e32 v97, 0, v97
	v_max_f32_e32 v90, 0, v90
	v_max_f32_e32 v91, 0, v91
	v_max_f32_e32 v92, 0, v92
	v_max_f32_e32 v93, 0, v93
	v_pk_mul_f32 v[94:95], v[94:95], v[94:95]
	v_pk_mul_f32 v[96:97], v[96:97], v[96:97]
	v_pk_mul_f32 v[90:91], v[90:91], v[90:91]
	v_pk_mul_f32 v[92:93], v[92:93], v[92:93]

.LBB0_1286:
	s_cmp_eq_u32 s19, 1
	s_cbranch_scc0 .LBB0_1288
	v_max_f32_e32 v86, 0, v86
	v_max_f32_e32 v87, 0, v87
	v_max_f32_e32 v88, 0, v88
	v_max_f32_e32 v89, 0, v89
	v_max_f32_e32 v82, 0, v82
	v_max_f32_e32 v83, 0, v83
	v_max_f32_e32 v84, 0, v84
	v_max_f32_e32 v85, 0, v85
	v_pk_mul_f32 v[86:87], v[86:87], v[86:87]
	v_pk_mul_f32 v[88:89], v[88:89], v[88:89]
	v_pk_mul_f32 v[82:83], v[82:83], v[82:83]
	v_pk_mul_f32 v[84:85], v[84:85], v[84:85]

.LBB0_1304:
	s_andn2_b64 vcc, exec, s[16:17]
	s_cbranch_vccnz .LBB0_1308
	s_cmp_eq_u32 s5, 1
	s_cbranch_scc0 .LBB0_1307
	v_max_f32_e32 v78, 0, v78
	v_max_f32_e32 v79, 0, v79
	v_max_f32_e32 v80, 0, v80
	v_max_f32_e32 v81, 0, v81
	v_max_f32_e32 v74, 0, v74
	v_max_f32_e32 v75, 0, v75
	v_max_f32_e32 v76, 0, v76
	v_max_f32_e32 v77, 0, v77
	v_pk_mul_f32 v[78:79], v[78:79], v[78:79]
	v_pk_mul_f32 v[80:81], v[80:81], v[80:81]
	v_pk_mul_f32 v[74:75], v[74:75], v[74:75]
	v_pk_mul_f32 v[76:77], v[76:77], v[76:77]

.LBB0_1314:
	s_cmp_eq_u32 s19, 1
	s_cbranch_scc0 .LBB0_1316
	v_max_f32_e32 v70, 0, v70
	v_max_f32_e32 v71, 0, v71
	v_max_f32_e32 v72, 0, v72
	v_max_f32_e32 v73, 0, v73
	v_max_f32_e32 v66, 0, v66
	v_max_f32_e32 v67, 0, v67
	v_max_f32_e32 v68, 0, v68
	v_max_f32_e32 v69, 0, v69
	v_pk_mul_f32 v[70:71], v[70:71], v[70:71]
	v_pk_mul_f32 v[72:73], v[72:73], v[72:73]
	v_pk_mul_f32 v[66:67], v[66:67], v[66:67]
	v_pk_mul_f32 v[68:69], v[68:69], v[68:69]

.LBB0_1332:
	s_andn2_b64 vcc, exec, s[16:17]
	s_cbranch_vccnz .LBB0_1336
	s_cmp_eq_u32 s5, 1
	s_cbranch_scc0 .LBB0_1335
	v_max_f32_e32 v62, 0, v62
	v_max_f32_e32 v63, 0, v63
	v_max_f32_e32 v64, 0, v64
	v_max_f32_e32 v65, 0, v65
	v_max_f32_e32 v58, 0, v58
	v_max_f32_e32 v59, 0, v59
	v_max_f32_e32 v60, 0, v60
	v_max_f32_e32 v61, 0, v61
	v_pk_mul_f32 v[62:63], v[62:63], v[62:63]
	v_pk_mul_f32 v[64:65], v[64:65], v[64:65]
	v_pk_mul_f32 v[58:59], v[58:59], v[58:59]
	v_pk_mul_f32 v[60:61], v[60:61], v[60:61]

.LBB0_1342:
	s_cmp_eq_u32 s19, 1
	s_cbranch_scc0 .LBB0_1344
	v_max_f32_e32 v54, 0, v54
	v_max_f32_e32 v55, 0, v55
	v_max_f32_e32 v56, 0, v56
	v_max_f32_e32 v57, 0, v57
	v_max_f32_e32 v50, 0, v50
	v_max_f32_e32 v51, 0, v51
	v_max_f32_e32 v52, 0, v52
	v_max_f32_e32 v53, 0, v53
	v_pk_mul_f32 v[54:55], v[54:55], v[54:55]
	v_pk_mul_f32 v[56:57], v[56:57], v[56:57]
	v_pk_mul_f32 v[50:51], v[50:51], v[50:51]
	v_pk_mul_f32 v[52:53], v[52:53], v[52:53]

.LBB0_1360:
	s_andn2_b64 vcc, exec, s[16:17]
	s_cbranch_vccnz .LBB0_1364
	s_cmp_eq_u32 s5, 1
	s_cbranch_scc0 .LBB0_1363
	v_max_f32_e32 v46, 0, v46
	v_max_f32_e32 v47, 0, v47
	v_max_f32_e32 v48, 0, v48
	v_max_f32_e32 v49, 0, v49
	v_max_f32_e32 v42, 0, v42
	v_max_f32_e32 v43, 0, v43
	v_max_f32_e32 v44, 0, v44
	v_max_f32_e32 v45, 0, v45
	v_pk_mul_f32 v[46:47], v[46:47], v[46:47]
	v_pk_mul_f32 v[48:49], v[48:49], v[48:49]
	v_pk_mul_f32 v[42:43], v[42:43], v[42:43]
	v_pk_mul_f32 v[44:45], v[44:45], v[44:45]

.LBB0_1370:
	s_cmp_eq_u32 s19, 1
	s_cbranch_scc0 .LBB0_1372
	v_max_f32_e32 v38, 0, v38
	v_max_f32_e32 v39, 0, v39
	v_max_f32_e32 v40, 0, v40
	v_max_f32_e32 v41, 0, v41
	v_max_f32_e32 v34, 0, v34
	v_max_f32_e32 v35, 0, v35
	v_max_f32_e32 v36, 0, v36
	v_max_f32_e32 v37, 0, v37
	v_pk_mul_f32 v[38:39], v[38:39], v[38:39]
	v_pk_mul_f32 v[40:41], v[40:41], v[40:41]
	v_pk_mul_f32 v[34:35], v[34:35], v[34:35]
	v_pk_mul_f32 v[36:37], v[36:37], v[36:37]

.LBB0_1388:
	s_andn2_b64 vcc, exec, s[16:17]
	s_cbranch_vccnz .LBB0_1392
	s_cmp_eq_u32 s5, 1
	s_cbranch_scc0 .LBB0_1391
	v_max_f32_e32 v30, 0, v30
	v_max_f32_e32 v31, 0, v31
	v_max_f32_e32 v32, 0, v32
	v_max_f32_e32 v33, 0, v33
	v_max_f32_e32 v26, 0, v26
	v_max_f32_e32 v27, 0, v27
	v_max_f32_e32 v28, 0, v28
	v_max_f32_e32 v29, 0, v29
	v_pk_mul_f32 v[30:31], v[30:31], v[30:31]
	v_pk_mul_f32 v[32:33], v[32:33], v[32:33]
	v_pk_mul_f32 v[26:27], v[26:27], v[26:27]
	v_pk_mul_f32 v[28:29], v[28:29], v[28:29]

.LBB0_1398:
	s_cmp_eq_u32 s19, 1
	s_cbranch_scc0 .LBB0_1400
	v_max_f32_e32 v22, 0, v22
	v_max_f32_e32 v23, 0, v23
	v_max_f32_e32 v24, 0, v24
	v_max_f32_e32 v25, 0, v25
	v_max_f32_e32 v18, 0, v18
	v_max_f32_e32 v19, 0, v19
	v_max_f32_e32 v20, 0, v20
	v_max_f32_e32 v21, 0, v21
	v_pk_mul_f32 v[22:23], v[22:23], v[22:23]
	v_pk_mul_f32 v[24:25], v[24:25], v[24:25]
	v_pk_mul_f32 v[18:19], v[18:19], v[18:19]
	v_pk_mul_f32 v[20:21], v[20:21], v[20:21]

.LBB0_1416:
	s_andn2_b64 vcc, exec, s[16:17]
	s_cbranch_vccnz .LBB0_1420
	s_cmp_eq_u32 s5, 1
	s_cbranch_scc0 .LBB0_1419
	v_max_f32_e32 v14, 0, v14
	v_max_f32_e32 v15, 0, v15
	v_max_f32_e32 v16, 0, v16
	v_max_f32_e32 v17, 0, v17
	v_max_f32_e32 v10, 0, v10
	v_max_f32_e32 v11, 0, v11
	v_max_f32_e32 v12, 0, v12
	v_max_f32_e32 v13, 0, v13
	v_pk_mul_f32 v[14:15], v[14:15], v[14:15]
	v_pk_mul_f32 v[16:17], v[16:17], v[16:17]
	v_pk_mul_f32 v[10:11], v[10:11], v[10:11]
	v_pk_mul_f32 v[12:13], v[12:13], v[12:13]

.LBB0_1426:
	s_cmp_eq_u32 s19, 1
	s_cbranch_scc0 .LBB0_1428
	v_max_f32_e32 v6, 0, v6
	v_max_f32_e32 v7, 0, v7
	v_max_f32_e32 v8, 0, v8
	v_max_f32_e32 v9, 0, v9
	v_max_f32_e32 v2, 0, v2
	v_max_f32_e32 v3, 0, v3
	v_max_f32_e32 v4, 0, v4
	v_max_f32_e32 v5, 0, v5
	v_pk_mul_f32 v[6:7], v[6:7], v[6:7]
	v_pk_mul_f32 v[8:9], v[8:9], v[8:9]
	v_pk_mul_f32 v[2:3], v[2:3], v[2:3]
	v_pk_mul_f32 v[4:5], v[4:5], v[4:5]
